# phase 0: s5_consts done by workgroups 248..255 (one transpose iteration, eight norm0 rows) instead of 0..7 (two, nine)
# speedup vs baseline: 1.0039x; 1.0039x over previous
.LBB0_75:
	s_mov_b32 s17, s2
	s_cmpk_lg_i32 s16, 0x200
	s_cbranch_scc1 .Ls5c_plain
	s_sub_u32 s17, s2, 0xf8
.Ls5c_plain:
	v_lshl_add_u32 v0, s17, 9, v129
	s_movk_i32 s3, 0x1000
	v_cmp_gt_u32_e32 vcc, s3, v0
	s_and_saveexec_b64 s[10:11], vcc
	s_load_dwordx16 s[68:83], s[0:1], 0x80
	s_cbranch_execz .LBB0_86
	s_load_dword s4, s[0:1], 0x148
	v_lshlrev_b32_e32 v1, 4, v129
	s_mov_b64 s[12:13], 0
	v_lshl_add_u32 v2, s17, 13, v1
	s_mov_b32 s19, 0x3fb8aa3b
	s_waitcnt lgkmcnt(0)
	s_lshl_b32 s3, s4, 9
	s_lshl_b32 s18, s4, 13
	s_mov_b32 s20, 0xc2ce8ed0
	s_mov_b32 s21, 0x42b17218
	v_mov_b32_e32 v6, 0x7f800000
	s_mov_b32 s26, 0xfe5163ab
	v_mov_b32_e32 v5, 0
	s_mov_b32 s27, 0x3c439041
	s_mov_b32 s28, 0xdb629599
	s_mov_b32 s29, 0xf534ddc0
	s_mov_b32 s30, 0xfc2757d1
	s_mov_b32 s31, 0x4e441529
	s_mov_b32 s34, 0xa2f9836e
	s_mov_b32 s35, 0x3fc90fda
	s_mov_b32 s54, 0xbfc90fda
	v_mov_b32_e32 v7, 0x3c0881c4
	v_mov_b32_e32 v8, 0xbab64f3b
	v_not_b32_e32 v9, 63
	v_not_b32_e32 v10, 31
	v_mov_b32_e32 v11, 0x7fc00000
	s_branch .LBB0_78
